# sel loop: running output kept in fixed registers (no per-tile copy in/out of the MFMA accumulators)
# speedup vs baseline: 1.1270x; 1.0163x over previous
; DI void task_nsa(const P& p, int layer, int task, bf16_t* sm, int dm) {
;     ...
;   for (int qi = 0; qi < 8; ++qi) {
;     const int qq = wv * 8 + qi, qpos = q0 + qq, j = lane, cur = qpos >> 6;
;     const float imp = cbuf[j * 65 + qq];
;     const bool valid = j <= cur;
;     const bool forced = (j == 0) || (j == cur) || (j == cur - 1);
;     const float score = valid ? imp + (forced ? 1e4f : 0.f) : -1e30f;
;     int rank = 0;
; #pragma unroll 4
;     for (int jp = 0; jp < 64; ++jp) {
;       const float sj = __int_as_float(__builtin_amdgcn_readlane(__float_as_int(score), jp));
;       rank += ((sj > score) || (sj == score && jp < j)) ? 1 : 0;
;     }
;     const unsigned long long mk = __ballot(rank < 16);
;     if (lane == 0) masks[qq] = mk;
;   }
;   __syncthreads();
;   const unsigned long long mymask = masks[ql];
;   unsigned long long un = 0ull;
;   for (int i = 0; i < 64; ++i) un |= masks[i];
;   {
;     const int cmax = qb;
;     unsigned long long todo = un & (cmax == 63 ? ~0ull : ((1ull << (cmax + 1)) - 1ull));
;     const bf16_t* kg = (const bf16_t*)(p.ws + O_KS) + (size_t)b * S_ * 128 + g * 64;
;     const bf16_t* vg = (const bf16_t*)(p.ws + O_VST) + (size_t)((b * 2 + g) * 64) * S_;
; #pragma unroll
;     for (int dt = 0; dt < 2; ++dt)
; #pragma unroll
;       for (int i = 0; i < 16; ++i) O[dt][i] = 0.f;
;     float m = -1e30f, l = 0.f;
;     kv_gload(R, kg, 128, vg, S_, (__ffsll((long long)todo) - 1) * 64);
.LBB0_713:
	v_readlane_b32 s2, v2, s6
	v_cmp_lt_u32_e64 s[4:5], s6, v129
	s_nop 0
	v_cmp_gt_f32_e64 s[0:1], s2, v2
	v_cmp_eq_f32_e64 s[2:3], s2, v2
	s_and_b64 s[2:3], s[2:3], s[4:5]
	s_add_i32 s4, s6, 1
	s_or_b64 s[0:1], s[0:1], s[2:3]
	v_readlane_b32 s2, v2, s4
	v_cndmask_b32_e64 v4, 0, 1, s[0:1]
	v_cmp_lt_u32_e64 s[4:5], s4, v129
	v_cmp_gt_f32_e64 s[0:1], s2, v2
	v_cmp_eq_f32_e64 s[2:3], s2, v2
	s_and_b64 s[2:3], s[2:3], s[4:5]
	s_or_b64 s[0:1], s[0:1], s[2:3]
	s_add_i32 s4, s6, 2
	v_addc_co_u32_e64 v3, s[0:1], v3, v4, s[0:1]
	v_readlane_b32 s2, v2, s4
	v_cmp_lt_u32_e64 s[4:5], s4, v129
	s_nop 0
	v_cmp_gt_f32_e64 s[0:1], s2, v2
	v_cmp_eq_f32_e64 s[2:3], s2, v2
	s_and_b64 s[2:3], s[2:3], s[4:5]
	s_add_i32 s4, s6, 3
	s_or_b64 s[0:1], s[0:1], s[2:3]
	v_readlane_b32 s2, v2, s4
	v_cndmask_b32_e64 v4, 0, 1, s[0:1]
	v_cmp_lt_u32_e64 s[4:5], s4, v129
	v_cmp_gt_f32_e64 s[0:1], s2, v2
	v_cmp_eq_f32_e64 s[2:3], s2, v2
	s_and_b64 s[2:3], s[2:3], s[4:5]
	s_or_b64 s[0:1], s[0:1], s[2:3]
	s_add_i32 s6, s6, 4
	v_addc_co_u32_e64 v3, s[0:1], v3, v4, s[0:1]
	s_cmp_lg_u32 s6, 64
	s_cbranch_scc1 .LBB0_713
	v_cmp_gt_u32_e64 s[2:3], 16, v3
	s_and_saveexec_b64 s[0:1], vcc
	s_nop 0
	v_mov_b64_e32 v[2:3], s[2:3]
	ds_write_b64 v1, v[2:3] offset:55864
	s_or_b64 exec, exec, s[0:1]
	v_add_u32_e32 v135, 0, v0
	v_lshl_add_u32 v0, v128, 3, 0
	s_waitcnt lgkmcnt(0)
	s_barrier
	ds_read_b64 v[96:97], v0 offset:55808
	ds_read_b128 v[0:3], v193 offset:55808
	ds_read_b128 v[4:7], v193 offset:55824
	ds_read_b128 v[8:11], v193 offset:55840
	ds_read_b128 v[12:15], v193 offset:55856
	s_waitcnt vmcnt(1)
	ds_read_b128 v[16:19], v193 offset:55872
	s_waitcnt vmcnt(0)
	ds_read_b128 v[20:23], v193 offset:55888
	ds_read_b128 v[24:27], v193 offset:55904
	ds_read_b128 v[28:31], v193 offset:55920
	ds_read_b128 v[32:35], v193 offset:55936
	ds_read_b128 v[36:39], v193 offset:55952
	ds_read_b128 v[40:43], v193 offset:55968
	ds_read_b128 v[44:47], v193 offset:55984
	ds_read_b128 v[48:51], v193 offset:56000
	ds_read_b128 v[52:55], v193 offset:56016
	ds_read_b128 v[56:59], v193 offset:56032
	ds_read_b128 v[60:63], v193 offset:56048
	ds_read_b128 v[80:83], v193 offset:56064
	ds_read_b128 v[84:87], v193 offset:56080
	ds_read_b128 v[98:101], v193 offset:56096
	ds_read_b128 v[102:105], v193 offset:56112
	ds_read_b128 v[106:109], v193 offset:56128
	ds_read_b128 v[110:113], v193 offset:56144
	ds_read_b128 v[114:117], v193 offset:56160
	ds_read_b128 v[118:121], v193 offset:56176
	ds_read_b128 v[122:125], v193 offset:56192
	ds_read_b128 v[126:129], v193 offset:56208
	ds_read_b128 v[140:143], v193 offset:56224
	ds_read_b128 v[144:147], v193 offset:56240
	ds_read_b128 v[148:151], v193 offset:56256
	ds_read_b128 v[152:155], v193 offset:56272
	ds_read_b128 v[156:159], v193 offset:56288
	ds_read_b128 v[160:163], v193 offset:56304
	s_waitcnt lgkmcnt(14)
	v_or_b32_e32 v0, v2, v0
	v_or_b32_e32 v1, v3, v1
	v_or_b32_e32 v0, v0, v4
	v_or_b32_e32 v1, v1, v5
	v_or_b32_e32 v0, v0, v6
	v_or_b32_e32 v1, v1, v7
	v_or_b32_e32 v0, v0, v8
	v_or_b32_e32 v1, v1, v9
	v_or_b32_e32 v0, v0, v10
	v_or_b32_e32 v1, v1, v11
	v_or_b32_e32 v0, v0, v12
	v_or_b32_e32 v1, v1, v13
	v_or_b32_e32 v0, v0, v14
	v_or_b32_e32 v1, v1, v15
	v_or_b32_e32 v0, v0, v16
	v_or_b32_e32 v1, v1, v17
	v_or_b32_e32 v0, v0, v18
	v_or_b32_e32 v1, v1, v19
	v_or_b32_e32 v0, v0, v20
	v_or_b32_e32 v1, v1, v21
	v_or_b32_e32 v0, v0, v22
	v_or_b32_e32 v1, v1, v23
	v_or_b32_e32 v0, v0, v24
	v_or_b32_e32 v1, v1, v25
	v_or_b32_e32 v0, v0, v26
	v_or_b32_e32 v1, v1, v27
	v_or_b32_e32 v0, v0, v28
	v_or_b32_e32 v1, v1, v29
	v_or_b32_e32 v0, v0, v30
	v_or_b32_e32 v1, v1, v31
	v_or_b32_e32 v0, v0, v32
	v_or_b32_e32 v1, v1, v33
	v_or_b32_e32 v0, v0, v34
	v_or_b32_e32 v1, v1, v35
	v_or_b32_e32 v0, v0, v36
	v_or_b32_e32 v1, v1, v37
	v_or_b32_e32 v0, v0, v38
	v_or_b32_e32 v1, v1, v39
	v_or_b32_e32 v0, v0, v40
	v_or_b32_e32 v1, v1, v41
	v_or_b32_e32 v0, v0, v42
	v_or_b32_e32 v1, v1, v43
	v_or_b32_e32 v0, v0, v44
	v_or_b32_e32 v1, v1, v45
	v_or_b32_e32 v0, v0, v46
	v_or_b32_e32 v1, v1, v47
	v_or_b32_e32 v0, v0, v48
	v_or_b32_e32 v1, v1, v49
	v_or_b32_e32 v0, v0, v50
	v_or_b32_e32 v1, v1, v51
	v_or_b32_e32 v0, v0, v52
	v_or_b32_e32 v1, v1, v53
	v_or_b32_e32 v0, v0, v54
	v_or_b32_e32 v1, v1, v55
	v_or_b32_e32 v0, v0, v56
	v_or_b32_e32 v1, v1, v57
	v_or_b32_e32 v0, v0, v58
	v_or_b32_e32 v1, v1, v59
	v_or_b32_e32 v0, v0, v60
	v_or_b32_e32 v1, v1, v61
	v_or_b32_e32 v0, v0, v62
	v_or_b32_e32 v1, v1, v63
	v_or_b32_e32 v0, v0, v80
	v_or_b32_e32 v1, v1, v81
	v_or_b32_e32 v0, v0, v82
	v_or_b32_e32 v1, v1, v83
	v_or_b32_e32 v0, v0, v84
	v_or_b32_e32 v1, v1, v85
	v_or_b32_e32 v0, v0, v86
	v_or_b32_e32 v1, v1, v87
	s_waitcnt lgkmcnt(13)
	v_or_b32_e32 v0, v0, v98
	v_or_b32_e32 v1, v1, v99
	v_or_b32_e32 v0, v0, v100
	v_or_b32_e32 v1, v1, v101
	s_waitcnt lgkmcnt(12)
	v_or_b32_e32 v0, v0, v102
	v_or_b32_e32 v1, v1, v103
	v_or_b32_e32 v0, v0, v104
	v_or_b32_e32 v1, v1, v105
	s_waitcnt lgkmcnt(11)
	v_or_b32_e32 v0, v0, v106
	v_or_b32_e32 v1, v1, v107
	v_or_b32_e32 v0, v0, v108
	v_or_b32_e32 v1, v1, v109
	s_waitcnt lgkmcnt(10)
	v_or_b32_e32 v0, v0, v110
	v_or_b32_e32 v1, v1, v111
	v_or_b32_e32 v0, v0, v112
	v_or_b32_e32 v1, v1, v113
	s_waitcnt lgkmcnt(9)
	v_or_b32_e32 v0, v0, v114
	v_or_b32_e32 v1, v1, v115
	v_or_b32_e32 v0, v0, v116
	v_or_b32_e32 v1, v1, v117
	s_waitcnt lgkmcnt(8)
	v_or_b32_e32 v0, v0, v118
	v_or_b32_e32 v1, v1, v119
	v_or_b32_e32 v0, v0, v120
	v_or_b32_e32 v1, v1, v121
	s_waitcnt lgkmcnt(7)
	v_or_b32_e32 v0, v0, v122
	v_or_b32_e32 v1, v1, v123
	v_or_b32_e32 v0, v0, v124
	v_or_b32_e32 v1, v1, v125
	s_waitcnt lgkmcnt(6)
	v_or_b32_e32 v0, v0, v126
	v_or_b32_e32 v1, v1, v127
	v_or_b32_e32 v0, v0, v128
	v_or_b32_e32 v1, v1, v129
	s_waitcnt lgkmcnt(5)
	v_or_b32_e32 v0, v0, v140
	v_or_b32_e32 v1, v1, v141
	v_or_b32_e32 v0, v0, v142
	v_or_b32_e32 v1, v1, v143
	s_waitcnt lgkmcnt(4)
	v_or_b32_e32 v0, v0, v144
	v_or_b32_e32 v1, v1, v145
	v_or_b32_e32 v0, v0, v146
	v_or_b32_e32 v1, v1, v147
	s_waitcnt lgkmcnt(3)
	v_or_b32_e32 v0, v0, v148
	v_or_b32_e32 v1, v1, v149
	v_or_b32_e32 v0, v0, v150
	v_or_b32_e32 v1, v1, v151
	s_waitcnt lgkmcnt(2)
	v_or_b32_e32 v0, v0, v152
	v_or_b32_e32 v1, v1, v153
	s_sub_i32 s0, 64, s45
	v_or_b32_e32 v0, v0, v154
	v_or_b32_e32 v1, v1, v155
	s_lshl_b64 s[0:1], -1, s0
	s_waitcnt lgkmcnt(1)
	v_or_b32_e32 v0, v0, v156
	v_or_b32_e32 v1, v1, v157
	s_add_i32 s39, s39, s47
	s_not_b64 s[0:1], s[0:1]
	v_or_b32_e32 v0, v0, v158
	v_or_b32_e32 v1, v1, v159
	s_cmp_gt_u32 s41, 7
	s_waitcnt lgkmcnt(0)
	v_or_b32_e32 v0, v0, v160
	v_or_b32_e32 v1, v1, v161
	s_cselect_b32 s1, s1, -1
	s_cselect_b32 s0, s0, -1
	v_or_b32_e32 v0, v0, v162
	v_or_b32_e32 v1, v1, v163
	v_and_b32_e32 v0, s0, v0
	v_and_b32_e32 v1, s1, v1
	v_add_u32_e32 v139, s25, v133
	v_cmp_eq_u64_e32 vcc, 0, v[0:1]
	s_lshl_b32 s44, s44, 19
	s_lshl_b32 s41, s40, 6
	s_lshl_b32 s40, s46, 18
	v_mov_b32_e32 v2, v195
	v_add_u32_e32 v137, 0xffffff41, v139
	v_or_b32_e32 v138, 31, v139
	s_cbranch_vccnz .LBB0_801
; DI void task_nsa(const P& p, int layer, int task, bf16_t* sm, int dm) {
;     ...
;     const bf16_t* kg = (const bf16_t*)(p.ws + O_KS) + (size_t)b * S_ * 128 + g * 64;
;     const bf16_t* vg = (const bf16_t*)(p.ws + O_VST) + (size_t)((b * 2 + g) * 64) * S_;
; #pragma unroll
;     for (int dt = 0; dt < 2; ++dt)
; #pragma unroll
;       for (int i = 0; i < 16; ++i) O[dt][i] = 0.f;
;     float m = -1e30f, l = 0.f;
;     kv_gload(R, kg, 128, vg, S_, (__ffsll((long long)todo) - 1) * 64);
	s_lshl_b32 s0, s44, 1
	v_readlane_b32 s2, v253, 40
	v_readlane_b32 s3, v253, 41
	s_add_u32 s0, s2, s0
	v_ashrrev_i32_e32 v4, 3, v2
	s_addc_u32 s1, s3, 0
	s_lshl_b32 s2, s41, 1
	v_ashrrev_i32_e32 v5, 31, v4
	s_add_u32 s0, s0, s2
	v_lshlrev_b64 v[6:7], 13, v[4:5]
	v_ffbl_b32_e32 v5, v1
	s_addc_u32 s1, s1, 0
	s_lshl_b32 s2, s40, 1
	v_readlane_b32 s4, v253, 38
	v_ffbl_b32_e32 v3, v0
	v_add_u32_e64 v5, v5, 32 clamp
	v_readlane_b32 s5, v253, 39
	s_add_u32 s6, s4, s2
	v_min_u32_e32 v5, v5, v3
	s_addc_u32 s7, s5, 0
	v_lshl_add_u32 v4, v5, 6, v4
	v_lshl_add_u64 v[6:7], s[6:7], 0, v[6:7]
	v_lshlrev_b32_e32 v192, 7, v5
	v_lshlrev_b32_e32 v2, 4, v2
	v_ashrrev_i32_e32 v5, 31, v4
	v_lshl_add_u64 v[6:7], v[6:7], 0, v[192:193]
	v_and_b32_e32 v192, 0x70, v2
	v_lshlrev_b64 v[4:5], 8, v[4:5]
	v_lshl_add_u64 v[2:3], v[6:7], 0, v[192:193]
	v_lshl_add_u64 v[4:5], s[0:1], 0, v[4:5]
	v_lshl_add_u64 v[4:5], v[4:5], 0, v[192:193]
	global_load_dwordx4 v[84:87], v[2:3], off
	global_load_dwordx4 v[80:83], v[4:5], off
	v_mov_b32_e32 v140, 0
	v_mov_b32_e32 v88, 0xf149f2ca
	v_mov_b32_e32 v130, 0
	v_mov_b32_e32 v131, v140
	v_mov_b32_e32 v128, 0
	v_mov_b32_e32 v129, v140
	v_mov_b32_e32 v126, 0
	v_mov_b32_e32 v127, v140
	v_mov_b32_e32 v124, 0
	v_mov_b32_e32 v125, v140
	v_mov_b32_e32 v116, 0
	v_mov_b32_e32 v117, v140
	v_mov_b32_e32 v112, 0
	v_mov_b32_e32 v113, v140
	v_mov_b32_e32 v110, 0
	v_mov_b32_e32 v111, v140
	v_mov_b32_e32 v108, 0
	v_mov_b32_e32 v109, v140
	v_mov_b32_e32 v122, 0
	v_mov_b32_e32 v123, v140
	v_mov_b32_e32 v120, 0
	v_mov_b32_e32 v121, v140
	v_mov_b32_e32 v118, 0
	v_mov_b32_e32 v119, v140
	v_mov_b32_e32 v114, 0
	v_mov_b32_e32 v115, v140
	v_mov_b32_e32 v106, 0
	v_mov_b32_e32 v107, v140
	v_mov_b32_e32 v104, 0
	v_mov_b32_e32 v105, v140
	v_mov_b32_e32 v102, 0
	v_mov_b32_e32 v103, v140
	v_mov_b32_e32 v100, 0
	v_mov_b32_e32 v101, v140
	v_mov_b64_e32 v[160:161], 0
	v_mov_b64_e32 v[162:163], 0
	v_mov_b64_e32 v[164:165], 0
	v_mov_b64_e32 v[166:167], 0
	v_mov_b64_e32 v[168:169], 0
	v_mov_b64_e32 v[170:171], 0
	v_mov_b64_e32 v[172:173], 0
	v_mov_b64_e32 v[174:175], 0
	v_mov_b64_e32 v[176:177], 0
	v_mov_b64_e32 v[178:179], 0
	v_mov_b64_e32 v[180:181], 0
	v_mov_b64_e32 v[182:183], 0
	v_mov_b64_e32 v[184:185], 0
	v_mov_b64_e32 v[186:187], 0
	v_mov_b64_e32 v[188:189], 0
	v_mov_b64_e32 v[190:191], 0

; template <int NDT, int MODE, bool ALLON>
; DI void attn_tile(const bf16_t* Kl, int kst, const bf16_t* Vl, const bf16x8 (&q)[4], f32x16 (&O)[NDT], float& m, float& l,
;                   int kbase, int qp, int win, float cbias, const float* tab, bool lane_on) {
;     ...
;   for (int ks = 0; ks < 4; ++ks) {
;     const bf16x8 k0 = *(const bf16x8*)(Kl + lr * kst + ks * 16 + lh * 8);
;     const bf16x8 k1 = *(const bf16x8*)(Kl + (32 + lr) * kst + ks * 16 + lh * 8);
;     s[0] = MFMA32(k0, q[ks], s[0]);
;     s[1] = MFMA32(k1, q[ks], s[1]);
;   }
;   float alpha, psum = 0.f;
;   if (MODE == 0) {
;     float tmax = fmaxf(s[0][0], s[1][0]);
; #pragma unroll
;     for (int i = 1; i < 16; ++i) tmax = fmaxf(tmax, fmaxf(s[0][i], s[1][i]));
;     tmax = fmaxf(tmax, xor32(tmax)) + cbias;
;     if (!ALLON) tmax = lane_on ? tmax : -1e30f;
;     const float mn = fmaxf(m, tmax);
;     alpha = ex2(m - mn);
;     m = mn;
;     const float mc = (ALLON || lane_on) ? mn - cbias : 1e30f;
; #pragma unroll
;     for (int st = 0; st < 2; ++st)
; #pragma unroll
;       for (int i = 0; i < 16; ++i) { const float pe = ex2(s[st][i] - mc); psum += pe; s[st][i] = pe; }
;   } else {
;     float tmax = -1e30f;
; #pragma unroll
;     for (int st = 0; st < 2; ++st)
; #pragma unroll
;       for (int i = 0; i < 16; ++i) {
;         const int key = kbase + st * 32 + 8 * (i >> 2) + 4 * lh + (i & 3);
;         float v;
;         if (MODE == 1) {
;           const int dist = qp - key;
;           const bool ok = (ALLON || lane_on) && dist >= 0 && dist < win;
;           const int di = dist < 0 ? 0 : (dist > 128 ? 128 : dist);
;           v = ok ? s[st][i] + tab[di] : -1e30f;
;         } else {
;           v = (16 * key + 31 <= qp) ? s[st][i] : -1e30f;
;         }
;         s[st][i] = v;
; DI void task_nsa(const P& p, int layer, int task, bf16_t* sm, int dm) {
;     ...
;     for (; todo; ++itc) {
;       const int j = __ffsll((long long)todo) - 1;
;       todo &= todo - 1ull;
;       bf16_t* Kl = sm + (itc & 1) * 9216; bf16_t* Vl = Kl + 4608;
;       kv_lstore(R, Kl, Vl);
;       if (todo) kv_gload(R, kg, 128, vg, S_, (__ffsll((long long)todo) - 1) * 64);
;       __syncthreads();
;       const bool on = (mymask >> j) & 1ull;
;       if (j * 64 <= qmin + 31 && __ballot(on)) {
;         if (j * 64 + 63 + 128 <= qmin)
;           attn_tile<2, 0, false>(Kl, 72, Vl, q, O, m, l, j * 64, qp, 0, tab[128], tab, on);
.LBB0_720:
	v_ffbl_b32_e32 v1, v1
	v_ffbl_b32_e32 v0, v0
	v_add_u32_e64 v1, v1, 32 clamp
	v_min_u32_e32 v0, v1, v0
	v_lshlrev_b32_e32 v32, 6, v0
	v_cmp_le_i32_e32 vcc, v32, v138
	s_waitcnt lgkmcnt(0)
	s_barrier
	s_and_saveexec_b64 s[8:9], vcc
	s_cbranch_execz .LBB0_797
	v_lshrrev_b64 v[0:1], v0, v[96:97]
	v_and_b32_e32 v0, 1, v0
	v_cmp_eq_u32_e64 s[4:5], 1, v0
	v_cmp_ne_u32_e32 vcc, 0, v0
	s_cbranch_vccz .LBB0_797
	v_cmp_le_i32_e32 vcc, v32, v137
	s_and_saveexec_b64 s[28:29], vcc
	s_xor_b64 s[28:29], exec, s[28:29]
	s_cbranch_execz .LBB0_727
	v_mov_b32_e32 v0, v195
	ds_read_b32 v144, v135 offset:37376
	s_nop 0
	v_and_b32_e32 v1, 31, v0
	v_lshrrev_b32_e32 v0, 2, v0
	v_mul_u32_u24_e32 v1, 0x48, v1
	v_and_b32_e32 v143, 8, v0
	v_lshlrev_b32_e32 v142, 1, v1
	v_lshlrev_b32_e32 v0, 1, v143
	v_add3_u32 v4, s45, v142, v0
	ds_read_b128 v[0:3], v4
	s_waitcnt lgkmcnt(0)
	v_mfma_f32_32x32x16_bf16 v[48:63], v[0:3], v[64:67], 0
	ds_read_b128 v[0:3], v4 offset:4608
	s_waitcnt lgkmcnt(0)
	v_mfma_f32_32x32x16_bf16 v[32:47], v[0:3], v[64:67], 0
	ds_read_b128 v[0:3], v4 offset:32
	s_waitcnt lgkmcnt(0)
	v_mfma_f32_32x32x16_bf16 v[48:63], v[0:3], v[68:71], v[48:63]
	ds_read_b128 v[0:3], v4 offset:4640
	s_waitcnt lgkmcnt(0)
	v_mfma_f32_32x32x16_bf16 v[32:47], v[0:3], v[68:71], v[32:47]
	ds_read_b128 v[0:3], v4 offset:64
	s_waitcnt lgkmcnt(0)
	v_mfma_f32_32x32x16_bf16 v[48:63], v[0:3], v[72:75], v[48:63]
	ds_read_b128 v[0:3], v4 offset:4672
	s_waitcnt lgkmcnt(0)
	v_mfma_f32_32x32x16_bf16 v[32:47], v[0:3], v[72:75], v[32:47]
	ds_read_b128 v[0:3], v4 offset:4704
	s_waitcnt lgkmcnt(0)
	v_mfma_f32_32x32x16_bf16 v[32:47], v[0:3], v[76:79], v[32:47]
	ds_read_b128 v[0:3], v4 offset:96
	s_waitcnt lgkmcnt(0)
	v_mfma_f32_32x32x16_bf16 v[48:63], v[0:3], v[76:79], v[48:63]
	s_nop 8
	v_max_f32_e32 v4, v33, v33
	v_max_f32_e32 v1, v34, v34
	s_nop 0
	v_max_f32_e32 v0, v49, v49
	v_max_f32_e32 v2, v50, v50
	v_max_f32_e32 v0, v0, v4
	v_max_f32_e32 v1, v2, v1
	v_max_f32_e32 v2, v35, v35
	v_max_f32_e32 v3, v51, v51
	v_max3_f32 v0, v48, v32, v0
	v_max_f32_e32 v2, v3, v2
	v_max3_f32 v0, v0, v1, v2
	v_max_f32_e32 v1, v36, v36
	v_max_f32_e32 v2, v52, v52
	v_max_f32_e32 v1, v2, v1
	v_max_f32_e32 v2, v37, v37
	v_max_f32_e32 v3, v53, v53
	v_max_f32_e32 v2, v3, v2
	v_max3_f32 v0, v0, v1, v2
	v_max_f32_e32 v1, v38, v38
	v_max_f32_e32 v2, v54, v54
	v_max_f32_e32 v1, v2, v1
	v_max_f32_e32 v2, v39, v39
	v_max_f32_e32 v3, v55, v55
	v_max_f32_e32 v2, v3, v2
	v_max3_f32 v0, v0, v1, v2
	v_max_f32_e32 v1, v40, v40
	v_max_f32_e32 v2, v56, v56
	v_max_f32_e32 v1, v2, v1
	v_max_f32_e32 v2, v41, v41
	v_max_f32_e32 v3, v57, v57
	v_max_f32_e32 v2, v3, v2
	v_max3_f32 v0, v0, v1, v2
	v_max_f32_e32 v1, v42, v42
	v_max_f32_e32 v2, v58, v58
	v_max_f32_e32 v1, v2, v1
	v_max_f32_e32 v2, v43, v43
	v_max_f32_e32 v3, v59, v59
	v_max_f32_e32 v2, v3, v2
	v_max3_f32 v0, v0, v1, v2
	v_max_f32_e32 v1, v44, v44
	v_max_f32_e32 v2, v60, v60
	v_max_f32_e32 v1, v2, v1
	v_max_f32_e32 v2, v45, v45
	v_max_f32_e32 v3, v61, v61
	v_max_f32_e32 v2, v3, v2
	v_max3_f32 v0, v0, v1, v2
	v_max_f32_e32 v1, v46, v46
	v_max_f32_e32 v2, v62, v62
	v_max_f32_e32 v1, v2, v1
	v_max_f32_e32 v2, v47, v47
	v_max_f32_e32 v3, v63, v63
	v_max_f32_e32 v2, v3, v2
	v_max3_f32 v0, v0, v1, v2
	ds_bpermute_b32 v1, v91, v0
	s_waitcnt lgkmcnt(0)
	v_max_f32_e32 v1, v1, v1
	v_max_f32_e32 v0, v0, v1
	v_add_f32_e32 v0, v144, v0
	v_cndmask_b32_e64 v0, v232, v0, s[4:5]
	v_max_f32_e32 v1, v88, v88
	v_max_f32_e32 v141, v1, v0
	v_sub_f32_e32 v0, v88, v141
	v_exp_f32_e32 v88, v0
	s_nop 0
	v_cmp_neq_f32_e32 vcc, 1.0, v88
	s_cbranch_vccz .LBB0_799
	v_pk_mul_f32 v[160:161], v[160:161], v[88:89] op_sel_hi:[1,0]
	v_pk_mul_f32 v[162:163], v[162:163], v[88:89] op_sel_hi:[1,0]
	v_pk_mul_f32 v[164:165], v[164:165], v[88:89] op_sel_hi:[1,0]
	v_pk_mul_f32 v[166:167], v[166:167], v[88:89] op_sel_hi:[1,0]
	v_pk_mul_f32 v[168:169], v[168:169], v[88:89] op_sel_hi:[1,0]
	v_pk_mul_f32 v[170:171], v[170:171], v[88:89] op_sel_hi:[1,0]
	v_pk_mul_f32 v[172:173], v[172:173], v[88:89] op_sel_hi:[1,0]
	v_pk_mul_f32 v[174:175], v[174:175], v[88:89] op_sel_hi:[1,0]
	v_pk_mul_f32 v[176:177], v[176:177], v[88:89] op_sel_hi:[1,0]
	v_pk_mul_f32 v[178:179], v[178:179], v[88:89] op_sel_hi:[1,0]
	v_pk_mul_f32 v[180:181], v[180:181], v[88:89] op_sel_hi:[1,0]
	v_pk_mul_f32 v[182:183], v[182:183], v[88:89] op_sel_hi:[1,0]
	v_pk_mul_f32 v[184:185], v[184:185], v[88:89] op_sel_hi:[1,0]
	v_pk_mul_f32 v[186:187], v[186:187], v[88:89] op_sel_hi:[1,0]
	v_pk_mul_f32 v[188:189], v[188:189], v[88:89] op_sel_hi:[1,0]
	v_pk_mul_f32 v[190:191], v[190:191], v[88:89] op_sel_hi:[1,0]
	s_cbranch_execnz .LBB0_726
; template <int NDT, int MODE, bool ALLON>
; DI void attn_tile(const bf16_t* Kl, int kst, const bf16_t* Vl, const bf16x8 (&q)[4], f32x16 (&O)[NDT], float& m, float& l,
;                   int kbase, int qp, int win, float cbias, const float* tab, bool lane_on) {
;     ...
;     alpha = ex2(m - mn);
;     m = mn;
;     const float mc = (ALLON || lane_on) ? mn - cbias : 1e30f;
; #pragma unroll
;     for (int st = 0; st < 2; ++st)
; #pragma unroll
;       for (int i = 0; i < 16; ++i) { const float pe = ex2(s[st][i] - mc); psum += pe; s[st][i] = pe; }
;   } else {
;     float tmax = -1e30f;
; #pragma unroll
;     for (int st = 0; st < 2; ++st)
; #pragma unroll
;       for (int i = 0; i < 16; ++i) {
;         const int key = kbase + st * 32 + 8 * (i >> 2) + 4 * lh + (i & 3);
;         float v;
;         if (MODE == 1) {
;           const int dist = qp - key;
;           const bool ok = (ALLON || lane_on) && dist >= 0 && dist < win;
;           const int di = dist < 0 ? 0 : (dist > 128 ? 128 : dist);
;           v = ok ? s[st][i] + tab[di] : -1e30f;
;         } else {
;           v = (16 * key + 31 <= qp) ? s[st][i] : -1e30f;
;         }
;         s[st][i] = v;
;         tmax = fmaxf(tmax, v);
;       }
;     tmax = fmaxf(tmax, xor32(tmax));
;     const float mn = fmaxf(m, tmax);
;     alpha = ex2(m - mn);
;     m = mn;
; #pragma unroll
;     for (int st = 0; st < 2; ++st)
; #pragma unroll
;       for (int i = 0; i < 16; ++i) {
;         const float pe = s[st][i] > -5e29f ? ex2(s[st][i] - mn) : 0.f;
;         psum += pe;
;         s[st][i] = pe;
;       }
;   }
;   l = l * alpha + psum;
;   if (__ballot(alpha != 1.f)) {
; #pragma unroll
;     for (int dt = 0; dt < NDT; ++dt)
; #pragma unroll
;       for (int i = 0; i < 16; ++i) O[dt][i] *= alpha;
;   }
; #pragma unroll
;   for (int st = 0; st < 2; ++st)
; #pragma unroll
;     for (int sk = 0; sk < 2; ++sk) {
;       u32x4 pu;
;       pu[0] = pack2(s[st][8 * sk + 0], s[st][8 * sk + 1]);
;       pu[1] = pack2(s[st][8 * sk + 2], s[st][8 * sk + 3]);
;       pu[2] = pack2(s[st][8 * sk + 4], s[st][8 * sk + 5]);
;       pu[3] = pack2(s[st][8 * sk + 6], s[st][8 * sk + 7]);
;       const bf16x8 pf = __builtin_bit_cast(bf16x8, pu);
; #pragma unroll
;       for (int dt = 0; dt < NDT; ++dt) {
;         const bf16_t* vp = Vl + (dt * 32 + lr) * 72 + st * 32 + sk * 16 + 4 * lh;
;         const uint2 v0 = *(const uint2*)(vp);
.LBB0_725:
.LBB0_726:
	v_sub_f32_e32 v100, v141, v144
	v_mov_b32_e32 v101, 0x7149f2ca
	v_cndmask_b32_e64 v100, v101, v100, s[4:5]
	v_sub_f32_e32 v48, v48, v100
	v_exp_f32_e32 v48, v48
	v_sub_f32_e32 v49, v49, v100
	v_exp_f32_e32 v49, v49
	v_sub_f32_e32 v50, v50, v100
	v_exp_f32_e32 v50, v50
	v_sub_f32_e32 v51, v51, v100
	v_exp_f32_e32 v51, v51
	v_sub_f32_e32 v52, v52, v100
	v_add_f32_e32 v101, 0, v48
	v_exp_f32_e32 v52, v52
	v_sub_f32_e32 v53, v53, v100
	v_add_f32_e32 v101, v49, v101
	v_exp_f32_e32 v53, v53
	v_sub_f32_e32 v54, v54, v100
	v_add_f32_e32 v101, v50, v101
	v_exp_f32_e32 v54, v54
	v_sub_f32_e32 v55, v55, v100
	v_add_f32_e32 v101, v51, v101
	v_exp_f32_e32 v55, v55
	v_sub_f32_e32 v56, v56, v100
	v_add_f32_e32 v101, v52, v101
	v_exp_f32_e32 v56, v56
	v_sub_f32_e32 v57, v57, v100
	v_add_f32_e32 v101, v53, v101
	v_exp_f32_e32 v57, v57
	v_sub_f32_e32 v58, v58, v100
	v_add_f32_e32 v101, v54, v101
	v_exp_f32_e32 v58, v58
	v_sub_f32_e32 v59, v59, v100
	v_add_f32_e32 v101, v55, v101
	v_exp_f32_e32 v59, v59
	v_sub_f32_e32 v60, v60, v100
	v_add_f32_e32 v101, v56, v101
	v_exp_f32_e32 v60, v60
	v_sub_f32_e32 v61, v61, v100
	v_add_f32_e32 v101, v57, v101
	v_exp_f32_e32 v61, v61
	v_sub_f32_e32 v62, v62, v100
	v_add_f32_e32 v101, v58, v101
	v_exp_f32_e32 v62, v62
	v_sub_f32_e32 v63, v63, v100
	v_add_f32_e32 v101, v59, v101
	v_exp_f32_e32 v63, v63
	v_sub_f32_e32 v32, v32, v100
	v_add_f32_e32 v101, v60, v101
	v_exp_f32_e32 v102, v32
	v_add_f32_e32 v101, v61, v101
	v_add_f32_e32 v101, v62, v101
	v_add_f32_e32 v101, v63, v101
	v_sub_f32_e32 v33, v33, v100
	v_add_f32_e32 v32, v102, v101
	v_exp_f32_e32 v101, v33
	v_sub_f32_e32 v33, v34, v100
	v_exp_f32_e32 v103, v33
	v_sub_f32_e32 v33, v35, v100
	v_exp_f32_e32 v104, v33
	v_sub_f32_e32 v33, v36, v100
	v_exp_f32_e32 v105, v33
	v_sub_f32_e32 v33, v37, v100
	v_add_f32_e32 v32, v101, v32
	v_exp_f32_e32 v37, v33
	v_sub_f32_e32 v33, v38, v100
	v_add_f32_e32 v32, v103, v32
	v_exp_f32_e32 v106, v33
	v_sub_f32_e32 v33, v39, v100
	v_add_f32_e32 v32, v104, v32
	v_exp_f32_e32 v107, v33
	v_sub_f32_e32 v33, v40, v100
	v_add_f32_e32 v32, v105, v32
	v_exp_f32_e32 v108, v33
	v_sub_f32_e32 v33, v41, v100
	v_add_f32_e32 v32, v37, v32
	v_exp_f32_e32 v109, v33
	v_sub_f32_e32 v33, v42, v100
	v_add_f32_e32 v32, v106, v32
	v_exp_f32_e32 v110, v33
	v_sub_f32_e32 v33, v43, v100
	v_add_f32_e32 v32, v107, v32
	v_exp_f32_e32 v111, v33
	v_sub_f32_e32 v33, v44, v100
	v_add_f32_e32 v32, v108, v32
	v_exp_f32_e32 v112, v33
	v_sub_f32_e32 v33, v45, v100
	v_add_f32_e32 v32, v109, v32
	v_exp_f32_e32 v113, v33
	v_sub_f32_e32 v33, v46, v100
	v_add_f32_e32 v32, v110, v32
	v_exp_f32_e32 v46, v33
	v_sub_f32_e32 v33, v47, v100
	v_add_f32_e32 v32, v111, v32
	v_exp_f32_e32 v47, v33
	v_add_f32_e32 v32, v112, v32
	v_add_f32_e32 v32, v113, v32
	v_add_f32_e32 v32, v46, v32
	v_add_f32_e32 v36, v47, v32
	v_cvt_pk_bf16_f32 v32, v48, v49
	v_add3_u32 v48, s45, v143, v142
	v_add_u32_e32 v49, 0x2000, v48
	ds_read2_b64 v[38:41], v49 offset0:128 offset1:130
	ds_read2_b64 v[42:45], v49 offset0:132 offset1:134
	v_cvt_pk_bf16_f32 v33, v50, v51
	v_cvt_pk_bf16_f32 v34, v52, v53
	v_cvt_pk_bf16_f32 v35, v54, v55
	v_add_u32_e32 v48, 0x3000, v48
	v_fmac_f32_e32 v36, v140, v88
	s_waitcnt lgkmcnt(1)
	v_mfma_f32_32x32x16_bf16 v[160:175], v[38:41], v[32:35], v[160:175]
	ds_read2_b64 v[38:41], v48 offset0:192 offset1:194
	s_waitcnt lgkmcnt(0)
	v_mfma_f32_32x32x16_bf16 v[176:191], v[38:41], v[32:35], v[176:191]
	ds_read2_b64 v[38:41], v48 offset0:196 offset1:198
	v_cvt_pk_bf16_f32 v32, v56, v57
	v_cvt_pk_bf16_f32 v33, v58, v59
	v_cvt_pk_bf16_f32 v34, v60, v61
	v_cvt_pk_bf16_f32 v35, v62, v63
	s_waitcnt lgkmcnt(0)
	s_nop 0
	v_mfma_f32_32x32x16_bf16 v[176:191], v[38:41], v[32:35], v[176:191]
	ds_read2_b64 v[38:41], v49 offset0:136 offset1:138
	v_mfma_f32_32x32x16_bf16 v[160:175], v[42:45], v[32:35], v[160:175]
	v_cvt_pk_bf16_f32 v32, v102, v101
	v_cvt_pk_bf16_f32 v33, v103, v104
	v_cvt_pk_bf16_f32 v34, v105, v37
	v_cvt_pk_bf16_f32 v35, v106, v107
	s_waitcnt lgkmcnt(0)
	s_nop 0
	v_mfma_f32_32x32x16_bf16 v[160:175], v[38:41], v[32:35], v[160:175]
	ds_read2_b64 v[38:41], v48 offset0:200 offset1:202
	s_waitcnt lgkmcnt(0)
	v_mfma_f32_32x32x16_bf16 v[176:191], v[38:41], v[32:35], v[176:191]
	ds_read2_b64 v[38:41], v49 offset0:140 offset1:142
	v_cvt_pk_bf16_f32 v32, v108, v109
	v_cvt_pk_bf16_f32 v33, v110, v111
	v_cvt_pk_bf16_f32 v34, v112, v113
	v_cvt_pk_bf16_f32 v35, v46, v47
	s_waitcnt lgkmcnt(0)
	s_nop 0
	v_mfma_f32_32x32x16_bf16 v[160:175], v[38:41], v[32:35], v[160:175]
	ds_read2_b64 v[38:41], v48 offset0:204 offset1:206
	s_waitcnt lgkmcnt(0)
	v_mfma_f32_32x32x16_bf16 v[176:191], v[38:41], v[32:35], v[176:191]

; DI float ex2(float x) { return __builtin_amdgcn_exp2f(x); }
; DI float xor32(float v) { return __shfl_xor(v, 32); }
; template <int NDT, int MODE, bool ALLON>
; DI void attn_tile(const bf16_t* Kl, int kst, const bf16_t* Vl, const bf16x8 (&q)[4], f32x16 (&O)[NDT], float& m, float& l,
;                   int kbase, int qp, int win, float cbias, const float* tab, bool lane_on) {
;     ...
;     float tmax = -1e30f;
; #pragma unroll
;     for (int st = 0; st < 2; ++st)
; #pragma unroll
;       for (int i = 0; i < 16; ++i) {
;         const int key = kbase + st * 32 + 8 * (i >> 2) + 4 * lh + (i & 3);
;         float v;
;         if (MODE == 1) {
;           const int dist = qp - key;
;           const bool ok = (ALLON || lane_on) && dist >= 0 && dist < win;
;           const int di = dist < 0 ? 0 : (dist > 128 ? 128 : dist);
;           v = ok ? s[st][i] + tab[di] : -1e30f;
;         } else {
;           v = (16 * key + 31 <= qp) ? s[st][i] : -1e30f;
;         }
;         s[st][i] = v;
;         tmax = fmaxf(tmax, v);
;       }
;     tmax = fmaxf(tmax, xor32(tmax));
;     const float mn = fmaxf(m, tmax);
;     alpha = ex2(m - mn);
;     m = mn;
; #pragma unroll
;     for (int st = 0; st < 2; ++st)
; #pragma unroll
;       for (int i = 0; i < 16; ++i) {
;         const float pe = s[st][i] > -5e29f ? ex2(s[st][i] - mn) : 0.f;
;         psum += pe;
;         s[st][i] = pe;
;       }
;   }
;   l = l * alpha + psum;
;   if (__ballot(alpha != 1.f)) {
; #pragma unroll
;     for (int dt = 0; dt < NDT; ++dt)
; #pragma unroll
;       for (int i = 0; i < 16; ++i) O[dt][i] *= alpha;
.LBB0_792:
	s_or_b64 exec, exec, s[4:5]
	v_max3_f32 v0, v62, s93, v55
	v_max3_f32 v0, v0, v61, v49
	v_max3_f32 v0, v0, v60, v47
	v_max3_f32 v0, v0, v59, v45
	v_max3_f32 v0, v0, v58, v43
	v_max3_f32 v0, v0, v57, v42
	v_max3_f32 v0, v0, v56, v41
	v_max3_f32 v0, v0, v54, v40
	v_max3_f32 v0, v0, v52, v39
	v_max3_f32 v0, v0, v51, v38
	v_max3_f32 v0, v0, v48, v37
	v_max3_f32 v0, v0, v46, v35
	v_max3_f32 v0, v0, v44, v36
	v_max3_f32 v0, v0, v53, v50
	v_max3_f32 v0, v0, v142, v63
	v_max3_f32 v0, v0, v144, v143
	ds_bpermute_b32 v1, v91, v0
	s_waitcnt lgkmcnt(0)
	v_max3_f32 v141, v88, v0, v1
	v_sub_f32_e32 v0, v88, v141
	v_exp_f32_e32 v32, v0
	s_nop 0
	v_cmp_neq_f32_e32 vcc, 1.0, v32
	s_cbranch_vccz .LBB0_800
	v_pk_mul_f32 v[160:161], v[160:161], v[32:33] op_sel_hi:[1,0]
	v_pk_mul_f32 v[162:163], v[162:163], v[32:33] op_sel_hi:[1,0]
	v_pk_mul_f32 v[164:165], v[164:165], v[32:33] op_sel_hi:[1,0]
	v_pk_mul_f32 v[166:167], v[166:167], v[32:33] op_sel_hi:[1,0]
	v_pk_mul_f32 v[168:169], v[168:169], v[32:33] op_sel_hi:[1,0]
	v_pk_mul_f32 v[170:171], v[170:171], v[32:33] op_sel_hi:[1,0]
	v_pk_mul_f32 v[172:173], v[172:173], v[32:33] op_sel_hi:[1,0]
	v_pk_mul_f32 v[174:175], v[174:175], v[32:33] op_sel_hi:[1,0]
	v_pk_mul_f32 v[176:177], v[176:177], v[32:33] op_sel_hi:[1,0]
	v_pk_mul_f32 v[178:179], v[178:179], v[32:33] op_sel_hi:[1,0]
	v_pk_mul_f32 v[180:181], v[180:181], v[32:33] op_sel_hi:[1,0]
	v_pk_mul_f32 v[182:183], v[182:183], v[32:33] op_sel_hi:[1,0]
	v_pk_mul_f32 v[184:185], v[184:185], v[32:33] op_sel_hi:[1,0]
	v_pk_mul_f32 v[186:187], v[186:187], v[32:33] op_sel_hi:[1,0]
	v_pk_mul_f32 v[188:189], v[188:189], v[32:33] op_sel_hi:[1,0]
	v_pk_mul_f32 v[190:191], v[190:191], v[32:33] op_sel_hi:[1,0]
	s_cbranch_execnz .LBB0_795
; #define MFMA32(a, b, c) __builtin_amdgcn_mfma_f32_32x32x16_bf16((a), (b), (c), 0, 0, 0)
; DI unsigned pack2(float a, float b) { f32x2_t v = {a, b}; bf16x2_t r = __builtin_convertvector(v, bf16x2_t); return __builtin_bit_cast(unsigned, r); }
; DI float ex2(float x) { return __builtin_amdgcn_exp2f(x); }
; template <int NDT, int MODE, bool ALLON>
; DI void attn_tile(const bf16_t* Kl, int kst, const bf16_t* Vl, const bf16x8 (&q)[4], f32x16 (&O)[NDT], float& m, float& l,
;                   int kbase, int qp, int win, float cbias, const float* tab, bool lane_on) {
;     ...
; #pragma unroll
;     for (int st = 0; st < 2; ++st)
; #pragma unroll
;       for (int i = 0; i < 16; ++i) {
;         const float pe = s[st][i] > -5e29f ? ex2(s[st][i] - mn) : 0.f;
;         psum += pe;
;         s[st][i] = pe;
;       }
;   }
;   l = l * alpha + psum;
;   if (__ballot(alpha != 1.f)) {
; #pragma unroll
;     for (int dt = 0; dt < NDT; ++dt)
; #pragma unroll
;       for (int i = 0; i < 16; ++i) O[dt][i] *= alpha;
;   }
; #pragma unroll
;   for (int st = 0; st < 2; ++st)
; #pragma unroll
;     for (int sk = 0; sk < 2; ++sk) {
;       u32x4 pu;
;       pu[0] = pack2(s[st][8 * sk + 0], s[st][8 * sk + 1]);
;       pu[1] = pack2(s[st][8 * sk + 2], s[st][8 * sk + 3]);
;       pu[2] = pack2(s[st][8 * sk + 4], s[st][8 * sk + 5]);
;       pu[3] = pack2(s[st][8 * sk + 6], s[st][8 * sk + 7]);
;       const bf16x8 pf = __builtin_bit_cast(bf16x8, pu);
; #pragma unroll
;       for (int dt = 0; dt < NDT; ++dt) {
;         const bf16_t* vp = Vl + (dt * 32 + lr) * 72 + st * 32 + sk * 16 + 4 * lh;
;         const uint2 v0 = *(const uint2*)(vp);
;         const uint2 v1 = *(const uint2*)(vp + 8);
;         u32x4 vu; vu[0] = v0.x; vu[1] = v0.y; vu[2] = v1.x; vu[3] = v1.y;
;         O[dt] = MFMA32(__builtin_bit_cast(bf16x8, vu), pf, O[dt]);
;       }
.LBB0_794:
.LBB0_795:
	v_cmp_lt_f32_e32 vcc, s11, v62
	v_sub_f32_e32 v62, v62, v141
	v_exp_f32_e32 v62, v62
	s_nop 0
	v_cndmask_b32_e32 v62, 0, v62, vcc
	v_cmp_lt_f32_e32 vcc, s11, v55
	v_sub_f32_e32 v55, v55, v141
	v_exp_f32_e32 v55, v55
	v_add_f32_e32 v88, 0, v62
	v_cndmask_b32_e32 v55, 0, v55, vcc
	v_cmp_lt_f32_e32 vcc, s11, v61
	v_sub_f32_e32 v61, v61, v141
	v_exp_f32_e32 v61, v61
	v_add_f32_e32 v88, v55, v88
	v_cndmask_b32_e32 v61, 0, v61, vcc
	v_cmp_lt_f32_e32 vcc, s11, v49
	v_sub_f32_e32 v49, v49, v141
	v_exp_f32_e32 v49, v49
	v_add_f32_e32 v88, v61, v88
	v_cndmask_b32_e32 v49, 0, v49, vcc
	v_cmp_lt_f32_e32 vcc, s11, v60
	v_sub_f32_e32 v60, v60, v141
	v_exp_f32_e32 v60, v60
	v_add_f32_e32 v88, v49, v88
	v_cvt_pk_bf16_f32 v49, v61, v49
	v_cndmask_b32_e32 v60, 0, v60, vcc
	v_cmp_lt_f32_e32 vcc, s11, v47
	v_sub_f32_e32 v47, v47, v141
	v_exp_f32_e32 v47, v47
	v_add_f32_e32 v100, v60, v88
	v_cndmask_b32_e32 v88, 0, v47, vcc
	v_cmp_lt_f32_e32 vcc, s11, v59
	v_sub_f32_e32 v59, v59, v141
	v_exp_f32_e32 v59, v59
	v_add_f32_e32 v47, v88, v100
	v_cndmask_b32_e32 v59, 0, v59, vcc
	v_cmp_lt_f32_e32 vcc, s11, v45
	v_sub_f32_e32 v45, v45, v141
	v_exp_f32_e32 v45, v45
	v_add_f32_e32 v47, v59, v47
	v_cndmask_b32_e32 v100, 0, v45, vcc
	v_sub_f32_e32 v45, v58, v141
	v_exp_f32_e32 v45, v45
	v_cmp_lt_f32_e32 vcc, s11, v58
	v_add_f32_e32 v47, v100, v47
	s_nop 0
	v_cndmask_b32_e32 v45, 0, v45, vcc
	v_cmp_lt_f32_e32 vcc, s11, v43
	v_sub_f32_e32 v43, v43, v141
	v_exp_f32_e32 v43, v43
	v_add_f32_e32 v47, v45, v47
	v_cndmask_b32_e32 v43, 0, v43, vcc
	v_add_f32_e32 v58, v43, v47
	v_sub_f32_e32 v47, v57, v141
	v_exp_f32_e32 v47, v47
	v_cmp_lt_f32_e32 vcc, s11, v57
	s_nop 1
	v_cndmask_b32_e32 v47, 0, v47, vcc
	v_cmp_lt_f32_e32 vcc, s11, v42
	v_sub_f32_e32 v42, v42, v141
	v_exp_f32_e32 v42, v42
	v_add_f32_e32 v57, v47, v58
	v_cndmask_b32_e32 v42, 0, v42, vcc
	v_cmp_lt_f32_e32 vcc, s11, v56
	v_sub_f32_e32 v56, v56, v141
	v_exp_f32_e32 v56, v56
	v_add_f32_e32 v57, v42, v57
	v_cndmask_b32_e32 v56, 0, v56, vcc
	v_cmp_lt_f32_e32 vcc, s11, v41
	v_sub_f32_e32 v41, v41, v141
	v_exp_f32_e32 v41, v41
	v_add_f32_e32 v57, v56, v57
	v_cndmask_b32_e32 v41, 0, v41, vcc
	v_cmp_lt_f32_e32 vcc, s11, v54
	v_sub_f32_e32 v54, v54, v141
	v_exp_f32_e32 v54, v54
	v_add_f32_e32 v57, v41, v57
	v_cndmask_b32_e32 v54, 0, v54, vcc
	v_cmp_lt_f32_e32 vcc, s11, v40
	v_sub_f32_e32 v40, v40, v141
	v_exp_f32_e32 v40, v40
	v_add_f32_e32 v57, v54, v57
	v_cndmask_b32_e32 v40, 0, v40, vcc
	v_cmp_lt_f32_e32 vcc, s11, v52
	v_sub_f32_e32 v52, v52, v141
	v_exp_f32_e32 v52, v52
	v_add_f32_e32 v57, v40, v57
	v_cndmask_b32_e32 v52, 0, v52, vcc
	v_cmp_lt_f32_e32 vcc, s11, v39
	v_sub_f32_e32 v39, v39, v141
	v_exp_f32_e32 v39, v39
	v_add_f32_e32 v57, v52, v57
	v_cndmask_b32_e32 v39, 0, v39, vcc
	v_cmp_lt_f32_e32 vcc, s11, v51
	v_sub_f32_e32 v51, v51, v141
	v_exp_f32_e32 v51, v51
	v_add_f32_e32 v57, v39, v57
	v_cndmask_b32_e32 v101, 0, v51, vcc
	v_cmp_lt_f32_e32 vcc, s11, v38
	v_sub_f32_e32 v38, v38, v141
	v_exp_f32_e32 v38, v38
	v_add_f32_e32 v51, v101, v57
	v_cndmask_b32_e32 v38, 0, v38, vcc
	v_cmp_lt_f32_e32 vcc, s11, v48
	v_sub_f32_e32 v48, v48, v141
	v_exp_f32_e32 v48, v48
	v_add_f32_e32 v51, v38, v51
	v_cndmask_b32_e32 v57, 0, v48, vcc
	v_cmp_lt_f32_e32 vcc, s11, v37
	v_sub_f32_e32 v37, v37, v141
	v_exp_f32_e32 v37, v37
	v_add_f32_e32 v48, v57, v51
	v_cvt_pk_bf16_f32 v51, v59, v100
	v_cndmask_b32_e32 v37, 0, v37, vcc
	v_cmp_lt_f32_e32 vcc, s11, v46
	v_sub_f32_e32 v46, v46, v141
	v_exp_f32_e32 v46, v46
	v_add_f32_e32 v48, v37, v48
	v_cndmask_b32_e32 v46, 0, v46, vcc
	v_cmp_lt_f32_e32 vcc, s11, v35
	v_sub_f32_e32 v35, v35, v141
	v_exp_f32_e32 v35, v35
	v_add_f32_e32 v48, v46, v48
	v_cndmask_b32_e32 v102, 0, v35, vcc
	v_cmp_lt_f32_e32 vcc, s11, v44
	v_sub_f32_e32 v44, v44, v141
	v_exp_f32_e32 v44, v44
	v_add_f32_e32 v35, v102, v48
	v_cvt_pk_bf16_f32 v48, v62, v55
	v_cndmask_b32_e32 v44, 0, v44, vcc
	v_cmp_lt_f32_e32 vcc, s11, v36
	v_sub_f32_e32 v36, v36, v141
	v_exp_f32_e32 v36, v36
	v_add_f32_e32 v35, v44, v35
	v_cndmask_b32_e32 v103, 0, v36, vcc
	v_sub_f32_e32 v36, v53, v141
	v_exp_f32_e32 v36, v36
	v_cmp_lt_f32_e32 vcc, s11, v53
	v_add_f32_e32 v35, v103, v35
	s_nop 0
	v_cndmask_b32_e32 v53, 0, v36, vcc
	v_sub_f32_e32 v36, v50, v141
	v_exp_f32_e32 v36, v36
	v_cmp_lt_f32_e32 vcc, s11, v50
	v_add_f32_e32 v35, v53, v35
	v_cvt_pk_bf16_f32 v50, v60, v88
	v_cndmask_b32_e32 v104, 0, v36, vcc
	v_sub_f32_e32 v36, v142, v141
	v_exp_f32_e32 v36, v36
	v_cmp_lt_f32_e32 vcc, s11, v142
	v_add_f32_e32 v35, v104, v35
	s_nop 0
	v_cndmask_b32_e32 v105, 0, v36, vcc
	v_sub_f32_e32 v36, v63, v141
	v_exp_f32_e32 v36, v36
	v_cmp_lt_f32_e32 vcc, s11, v63
	v_add_f32_e32 v35, v105, v35
	s_nop 0
	v_cndmask_b32_e32 v63, 0, v36, vcc
	v_sub_f32_e32 v36, v144, v141
	v_exp_f32_e32 v36, v36
	v_cmp_lt_f32_e32 vcc, s11, v144
	v_add_f32_e32 v35, v63, v35
	s_nop 0
	v_cndmask_b32_e32 v106, 0, v36, vcc
	v_sub_f32_e32 v36, v143, v141
	v_exp_f32_e32 v36, v36
	v_cmp_lt_f32_e32 vcc, s11, v143
	v_add_f32_e32 v35, v106, v35
	s_nop 0
	v_cndmask_b32_e32 v107, 0, v36, vcc
	v_add_f32_e32 v36, v107, v35
	v_fmac_f32_e32 v36, v140, v32
	v_lshlrev_b32_e32 v32, 1, v34
	v_add3_u32 v55, s45, v32, v33
	v_add_u32_e32 v62, 0x2000, v55
	ds_read2_b64 v[32:35], v62 offset0:128 offset1:130
	ds_read2_b64 v[58:61], v62 offset0:132 offset1:134
	v_add_u32_e32 v55, 0x3000, v55
	s_waitcnt lgkmcnt(1)
	v_mfma_f32_32x32x16_bf16 v[160:175], v[32:35], v[48:51], v[160:175]
	ds_read2_b64 v[32:35], v55 offset0:192 offset1:194
	s_waitcnt lgkmcnt(0)
	v_mfma_f32_32x32x16_bf16 v[176:191], v[32:35], v[48:51], v[176:191]
	v_cvt_pk_bf16_f32 v32, v45, v43
	v_cvt_pk_bf16_f32 v33, v47, v42
	v_cvt_pk_bf16_f32 v34, v56, v41
	v_cvt_pk_bf16_f32 v35, v54, v40
	ds_read2_b64 v[40:43], v55 offset0:196 offset1:198
	s_nop 0
	v_mfma_f32_32x32x16_bf16 v[160:175], v[58:61], v[32:35], v[160:175]
	s_waitcnt lgkmcnt(0)
	v_mfma_f32_32x32x16_bf16 v[176:191], v[40:43], v[32:35], v[176:191]
	v_cvt_pk_bf16_f32 v32, v52, v39
	v_cvt_pk_bf16_f32 v33, v101, v38
	ds_read2_b64 v[38:41], v62 offset0:136 offset1:138
	v_cvt_pk_bf16_f32 v34, v57, v37
	v_cvt_pk_bf16_f32 v35, v46, v102
	s_waitcnt lgkmcnt(0)
	s_nop 0
	v_mfma_f32_32x32x16_bf16 v[160:175], v[38:41], v[32:35], v[160:175]
	ds_read2_b64 v[38:41], v55 offset0:200 offset1:202
	s_waitcnt lgkmcnt(0)
	v_mfma_f32_32x32x16_bf16 v[176:191], v[38:41], v[32:35], v[176:191]
	ds_read2_b64 v[38:41], v62 offset0:140 offset1:142
	v_cvt_pk_bf16_f32 v32, v44, v103
	v_cvt_pk_bf16_f32 v33, v53, v104
	v_cvt_pk_bf16_f32 v34, v105, v63
	v_cvt_pk_bf16_f32 v35, v106, v107
	s_waitcnt lgkmcnt(0)
	s_nop 0
	v_mfma_f32_32x32x16_bf16 v[160:175], v[38:41], v[32:35], v[160:175]
	ds_read2_b64 v[38:41], v55 offset0:204 offset1:206
	s_waitcnt lgkmcnt(0)
	v_mfma_f32_32x32x16_bf16 v[176:191], v[38:41], v[32:35], v[176:191]
.LBB0_796:
	s_or_b64 exec, exec, s[28:29]
	s_nop 0
	v_mov_b32_e32 v140, v36
	v_mov_b32_e32 v88, v141

; DI float xor32(float v) { return __shfl_xor(v, 32); }
; DI void task_nsa(const P& p, int layer, int task, bf16_t* sm, int dm) {
;     ...
;     const float lt = l + xor32(l);
;     const float inv = lt > 0.f ? 1.f / lt : 0.f;
;     {
;       const float sc = g1 * inv;
; #pragma unroll
;       for (int dt = 0; dt < 2; ++dt)
; #pragma unroll
;         for (int i = 0; i < 16; ++i) outl[(dt * 16 + i) * 64] += sc * O[dt][i];
;     }
.Lsel_home_exit:
	v_mov_b32_e32 v100, v190
	v_mov_b32_e32 v101, v191
	v_mov_b32_e32 v102, v188
	v_mov_b32_e32 v103, v189
	v_mov_b32_e32 v104, v186
	v_mov_b32_e32 v105, v187
	v_mov_b32_e32 v106, v184
	v_mov_b32_e32 v107, v185
	v_mov_b32_e32 v108, v174
	v_mov_b32_e32 v109, v175
	v_mov_b32_e32 v110, v172
	v_mov_b32_e32 v111, v173
	v_mov_b32_e32 v112, v170
	v_mov_b32_e32 v113, v171
	v_mov_b32_e32 v114, v182
	v_mov_b32_e32 v115, v183
	v_mov_b32_e32 v116, v168
	v_mov_b32_e32 v117, v169
	v_mov_b32_e32 v118, v180
	v_mov_b32_e32 v119, v181
	v_mov_b32_e32 v120, v178
	v_mov_b32_e32 v121, v179
	v_mov_b32_e32 v122, v176
	v_mov_b32_e32 v123, v177
	v_mov_b32_e32 v124, v166
	v_mov_b32_e32 v125, v167
	v_mov_b32_e32 v126, v164
	v_mov_b32_e32 v127, v165
	v_mov_b32_e32 v128, v162
	v_mov_b32_e32 v129, v163
	v_mov_b32_e32 v130, v160
	v_mov_b32_e32 v131, v161
	s_branch .LBB0_802
